# attention body: QK MFMA clusters at priority 3, softmax and PV streams at 2, loop top at 0
# baseline (speedup 1.0000x reference)
.LBB0_452:
	s_setprio 3
	v_add3_u32 v197, s54, v190, v215
	ds_read_b128 v[68:71], v197
	ds_read_b128 v[72:75], v197 offset:32
	ds_read_b128 v[76:79], v197 offset:64
	ds_read_b128 v[80:83], v197 offset:96
	ds_read_b128 v[84:87], v197 offset:4608
	ds_read_b128 v[88:91], v197 offset:4640
	ds_read_b128 v[92:95], v197 offset:4672
	ds_read_b128 v[96:99], v197 offset:4704
	v_lshl_add_u64 v[136:137], v[198:199], 0, s[16:17]
	v_add_co_u32_e32 v138, vcc, 0xdee2000, v136
	s_nop 1
	v_addc_co_u32_e32 v139, vcc, 0, v137, vcc
	v_add_co_u32_e32 v140, vcc, 0xdee3000, v136
	s_nop 1
	v_addc_co_u32_e32 v141, vcc, 0, v137, vcc
	global_load_dwordx4 v[136:139], v[138:139], off
	s_nop 0
	global_load_dwordx4 v[140:143], v[140:141], off
	s_waitcnt lgkmcnt(7)
	v_mfma_f32_32x32x16_bf16 v[100:115], v[68:71], v[132:135], 0
	v_lshl_add_u64 v[66:67], v[200:201], 0, s[16:17]
	v_add_co_u32_e32 v144, vcc, 0xe3de000, v66
	s_waitcnt lgkmcnt(6)
	v_mfma_f32_32x32x16_bf16 v[100:115], v[72:75], v[156:159], v[100:115]
	s_nop 1
	v_addc_co_u32_e32 v145, vcc, 0, v67, vcc
	s_waitcnt lgkmcnt(5)
	v_mfma_f32_32x32x16_bf16 v[100:115], v[76:79], v[152:155], v[100:115]
	v_add_co_u32_e32 v66, vcc, 0xe422000, v66
	s_nop 1
	s_waitcnt lgkmcnt(4)
	v_mfma_f32_32x32x16_bf16 v[100:115], v[80:83], v[148:151], v[100:115]
	v_addc_co_u32_e32 v67, vcc, 0, v67, vcc
	global_load_dwordx4 v[176:179], v[144:145], off offset:256
	s_waitcnt lgkmcnt(3)
	v_mfma_f32_32x32x16_bf16 v[116:131], v[84:87], v[132:135], 0
	s_nop 0
	global_load_dwordx4 v[144:147], v[66:67], off offset:256
	s_waitcnt lgkmcnt(2)
	v_mfma_f32_32x32x16_bf16 v[116:131], v[88:91], v[156:159], v[116:131]
	v_add3_u32 v210, s54, v188, v65
	v_add_u32_e32 v211, 0x3000, v210
	s_waitcnt lgkmcnt(1)
	v_mfma_f32_32x32x16_bf16 v[116:131], v[92:95], v[152:155], v[116:131]
	v_add_u32_e32 v210, 0x2000, v210
	s_waitcnt lgkmcnt(0)
	v_mfma_f32_32x32x16_bf16 v[116:131], v[96:99], v[148:151], v[116:131]
	ds_read_b128 v[202:205], v197 offset:4608
	ds_read_b128 v[206:209], v197 offset:4640
	ds_read_b128 v[218:221], v197 offset:4672
	v_mfma_f32_32x32x16_bf16 v[84:99], v[68:71], v[172:175], 0
	v_max3_f32 v67, v100, v101, v102
	v_max3_f32 v67, v67, v103, v104
	v_mfma_f32_32x32x16_bf16 v[84:99], v[72:75], v[168:171], v[84:99]
	v_max3_f32 v67, v67, v105, v106
	v_max3_f32 v67, v67, v107, v108
	v_mfma_f32_32x32x16_bf16 v[84:99], v[76:79], v[164:167], v[84:99]
	v_max3_f32 v67, v67, v109, v110
	v_max3_f32 v67, v67, v111, v112
	v_mfma_f32_32x32x16_bf16 v[84:99], v[80:83], v[160:163], v[84:99]
	v_max3_f32 v67, v67, v113, v114
	v_max_f32_e32 v67, v67, v115
	s_waitcnt lgkmcnt(2)
	v_mfma_f32_32x32x16_bf16 v[68:83], v[202:205], v[172:175], 0
	ds_read_b128 v[202:205], v197 offset:4704
	v_max3_f32 v182, v116, v117, v118
	v_max3_f32 v182, v182, v119, v120
	v_max3_f32 v182, v182, v121, v122
	v_max3_f32 v182, v182, v123, v124
	s_waitcnt lgkmcnt(2)
	v_mfma_f32_32x32x16_bf16 v[68:83], v[206:209], v[168:171], v[68:83]
	v_max3_f32 v182, v182, v125, v126
	v_max3_f32 v182, v182, v127, v128
	v_max3_f32 v182, v182, v129, v130
	v_max_f32_e32 v182, v182, v131
	v_max_f32_e32 v67, v67, v182
	ds_bpermute_b32 v182, v191, v67
	s_waitcnt lgkmcnt(2)
	v_mfma_f32_32x32x16_bf16 v[68:83], v[218:221], v[164:167], v[68:83]
	s_waitcnt lgkmcnt(1)
	v_mfma_f32_32x32x16_bf16 v[68:83], v[202:205], v[160:163], v[68:83]
	s_setprio 2
	ds_read2_b64 v[206:209], v210 offset0:128 offset1:130
	ds_read2_b64 v[218:221], v211 offset0:160 offset1:162
	s_waitcnt lgkmcnt(2)
	v_max3_f32 v66, v216, v67, v182
	v_cmp_gt_f32_e32 vcc, v66, v216
	s_cbranch_vccz .Lattn_keep0
	v_sub_f32_e32 v182, v216, v66
	v_exp_f32_e32 v182, v182
	s_nop 0
	v_pk_mul_f32 v[48:49], v[48:49], v[182:183] op_sel_hi:[1,0]
	v_pk_mul_f32 v[50:51], v[50:51], v[182:183] op_sel_hi:[1,0]
	v_pk_mul_f32 v[52:53], v[52:53], v[182:183] op_sel_hi:[1,0]
	v_pk_mul_f32 v[54:55], v[54:55], v[182:183] op_sel_hi:[1,0]
	v_pk_mul_f32 v[56:57], v[56:57], v[182:183] op_sel_hi:[1,0]
	v_pk_mul_f32 v[58:59], v[58:59], v[182:183] op_sel_hi:[1,0]
	v_pk_mul_f32 v[60:61], v[60:61], v[182:183] op_sel_hi:[1,0]
	v_pk_mul_f32 v[62:63], v[62:63], v[182:183] op_sel_hi:[1,0]
	v_pk_mul_f32 v[16:17], v[16:17], v[182:183] op_sel_hi:[1,0]
	v_pk_mul_f32 v[18:19], v[18:19], v[182:183] op_sel_hi:[1,0]
	v_pk_mul_f32 v[20:21], v[20:21], v[182:183] op_sel_hi:[1,0]
	v_pk_mul_f32 v[22:23], v[22:23], v[182:183] op_sel_hi:[1,0]
	v_pk_mul_f32 v[24:25], v[24:25], v[182:183] op_sel_hi:[1,0]
	v_pk_mul_f32 v[26:27], v[26:27], v[182:183] op_sel_hi:[1,0]
	v_pk_mul_f32 v[28:29], v[28:29], v[182:183] op_sel_hi:[1,0]
	v_pk_mul_f32 v[30:31], v[30:31], v[182:183] op_sel_hi:[1,0]
	v_mul_f32_e32 v194, v194, v182
